# mixer remap + local seams 3,10, with all neighbour WAR dependencies (seams 1,4,6,8,11) deferred to the first overlay store
# speedup vs baseline: 1.0082x; 1.0021x over previous
.LBB0_459:
	s_add_u32 s14, s48, 0xfffc0080
	s_addc_u32 s15, s49, -1
	s_add_i32 s70, 0, 0x10000
	s_cmp_eq_u32 s51, 12
	s_cselect_b32 s15, s31, s15
	s_cselect_b32 s14, s43, s14
	v_add_u32_e32 v138, s70, v142
	s_cselect_b32 s61, s13, s17
	s_cselect_b32 s60, s50, s16
	s_add_i32 s84, 0, 0x14000
	ds_read_b128 v[134:137], v138
	ds_read_b128 v[148:151], v138 offset:1024
	ds_read_b128 v[152:155], v138 offset:2048
	ds_read_b128 v[156:159], v138 offset:3072
	v_add_u32_e32 v138, s84, v142
	ds_read_b128 v[160:163], v138
	ds_read_b128 v[164:167], v138 offset:1024
	ds_read_b128 v[168:171], v138 offset:2048
	ds_read_b128 v[172:175], v138 offset:3072
	v_lshl_add_u64 v[138:139], s[48:49], 0, v[132:133]
	s_add_i32 m0, s19, 0xc000
	ds_read_b128 v[176:179], v146
	ds_read_b128 v[180:183], v146 offset:1024
	ds_read_b128 v[194:197], v146 offset:2048
	ds_read_b128 v[198:201], v146 offset:3072
	ds_read_b128 v[202:205], v146 offset:4096
	ds_read_b128 v[206:209], v146 offset:5120
	ds_read_b128 v[210:213], v146 offset:6144
	ds_read_b128 v[214:217], v146 offset:7168
	global_load_lds_dwordx4 v[138:139], off
	v_lshl_add_u64 v[138:139], v[138:139], 0, s[34:35]
	s_add_i32 m0, s19, 0xe000
	s_nop 0
	global_load_lds_dwordx4 v[138:139], off
	s_waitcnt vmcnt(8)
	s_waitcnt lgkmcnt(0)
	s_barrier
	s_setprio 1
	s_waitcnt lgkmcnt(0)
	v_mfma_f32_16x16x32_bf16 v[124:127], v[134:137], v[176:179], v[124:127]
	v_mfma_f32_16x16x32_bf16 v[116:119], v[152:155], v[176:179], v[116:119]
	v_mfma_f32_16x16x32_bf16 v[108:111], v[134:137], v[194:197], v[108:111]
	v_mfma_f32_16x16x32_bf16 v[100:103], v[152:155], v[194:197], v[100:103]
	v_mfma_f32_16x16x32_bf16 v[92:95], v[134:137], v[202:205], v[92:95]
	v_mfma_f32_16x16x32_bf16 v[84:87], v[152:155], v[202:205], v[84:87]
	v_mfma_f32_16x16x32_bf16 v[76:79], v[134:137], v[210:213], v[76:79]
	v_mfma_f32_16x16x32_bf16 v[68:71], v[152:155], v[210:213], v[68:71]
	v_mfma_f32_16x16x32_bf16 v[124:127], v[148:151], v[180:183], v[124:127]
	v_mfma_f32_16x16x32_bf16 v[116:119], v[156:159], v[180:183], v[116:119]
	v_mfma_f32_16x16x32_bf16 v[108:111], v[148:151], v[198:201], v[108:111]
	v_mfma_f32_16x16x32_bf16 v[100:103], v[156:159], v[198:201], v[100:103]
	v_mfma_f32_16x16x32_bf16 v[92:95], v[148:151], v[206:209], v[92:95]
	v_mfma_f32_16x16x32_bf16 v[84:87], v[156:159], v[206:209], v[84:87]
	v_mfma_f32_16x16x32_bf16 v[76:79], v[148:151], v[214:217], v[76:79]
	v_mfma_f32_16x16x32_bf16 v[68:71], v[156:159], v[214:217], v[68:71]
	s_setprio 0
	s_setprio 1
	v_mfma_f32_16x16x32_bf16 v[120:123], v[160:163], v[176:179], v[120:123]
	v_mfma_f32_16x16x32_bf16 v[112:115], v[168:171], v[176:179], v[112:115]
	v_mfma_f32_16x16x32_bf16 v[104:107], v[160:163], v[194:197], v[104:107]
	v_mfma_f32_16x16x32_bf16 v[96:99], v[168:171], v[194:197], v[96:99]
	v_mfma_f32_16x16x32_bf16 v[88:91], v[160:163], v[202:205], v[88:91]
	v_mfma_f32_16x16x32_bf16 v[80:83], v[168:171], v[202:205], v[80:83]
	v_mfma_f32_16x16x32_bf16 v[72:75], v[160:163], v[210:213], v[72:75]
	v_mfma_f32_16x16x32_bf16 v[64:67], v[168:171], v[210:213], v[64:67]
	v_mfma_f32_16x16x32_bf16 v[120:123], v[164:167], v[180:183], v[120:123]
	v_mfma_f32_16x16x32_bf16 v[112:115], v[172:175], v[180:183], v[112:115]
	v_mfma_f32_16x16x32_bf16 v[104:107], v[164:167], v[198:201], v[104:107]
	v_mfma_f32_16x16x32_bf16 v[96:99], v[172:175], v[198:201], v[96:99]
	v_mfma_f32_16x16x32_bf16 v[88:91], v[164:167], v[206:209], v[88:91]
	v_mfma_f32_16x16x32_bf16 v[80:83], v[172:175], v[206:209], v[80:83]
	v_mfma_f32_16x16x32_bf16 v[72:75], v[164:167], v[214:217], v[72:75]
	v_mfma_f32_16x16x32_bf16 v[64:67], v[172:175], v[214:217], v[64:67]
	s_setprio 0
	s_barrier
	v_lshl_add_u64 v[138:139], s[60:61], 0, v[184:185]
	s_add_i32 s60, s70, s6
	s_mov_b32 m0, s60
	ds_read_b128 v[176:179], v146 offset:16384
	ds_read_b128 v[180:183], v146 offset:17408
	ds_read_b128 v[194:197], v146 offset:18432
	ds_read_b128 v[198:201], v146 offset:19456
	ds_read_b128 v[202:205], v146 offset:20480
	ds_read_b128 v[206:209], v146 offset:21504
	ds_read_b128 v[210:213], v146 offset:22528
	ds_read_b128 v[214:217], v146 offset:23552
	global_load_lds_dwordx4 v[138:139], off
	v_lshl_add_u64 v[218:219], v[138:139], 0, s[34:35]
	s_add_i32 m0, s60, 0x2000
	s_add_i32 s60, s84, s6
	global_load_lds_dwordx4 v[218:219], off
	v_lshl_add_u64 v[218:219], v[138:139], 0, s[92:93]
	s_mov_b32 m0, s60
	s_nop 0
	global_load_lds_dwordx4 v[218:219], off
	v_lshl_add_u64 v[218:219], v[138:139], 0, s[52:53]
	s_add_i32 m0, s60, 0x2000
	s_nop 0
	global_load_lds_dwordx4 v[218:219], off
	v_lshl_add_u64 v[218:219], s[14:15], 0, v[128:129]
	s_mov_b32 m0, s19
	v_lshl_add_u64 v[220:221], v[218:219], 0, s[34:35]
	global_load_lds_dwordx4 v[218:219], off
	s_mov_b32 m0, s20
	s_nop 0
	global_load_lds_dwordx4 v[220:221], off
	s_waitcnt vmcnt(8)
	s_waitcnt lgkmcnt(0)
	s_barrier
	s_setprio 1
	s_waitcnt lgkmcnt(0)
	v_mfma_f32_16x16x32_bf16 v[60:63], v[134:137], v[176:179], v[60:63]
	v_mfma_f32_16x16x32_bf16 v[52:55], v[152:155], v[176:179], v[52:55]
	v_mfma_f32_16x16x32_bf16 v[44:47], v[134:137], v[194:197], v[44:47]
	v_mfma_f32_16x16x32_bf16 v[36:39], v[152:155], v[194:197], v[36:39]
	v_mfma_f32_16x16x32_bf16 v[28:31], v[134:137], v[202:205], v[28:31]
	v_mfma_f32_16x16x32_bf16 v[20:23], v[152:155], v[202:205], v[20:23]
	v_mfma_f32_16x16x32_bf16 v[12:15], v[134:137], v[210:213], v[12:15]
	v_mfma_f32_16x16x32_bf16 v[4:7], v[152:155], v[210:213], v[4:7]
	v_mfma_f32_16x16x32_bf16 v[60:63], v[148:151], v[180:183], v[60:63]
	v_mfma_f32_16x16x32_bf16 v[52:55], v[156:159], v[180:183], v[52:55]
	v_mfma_f32_16x16x32_bf16 v[44:47], v[148:151], v[198:201], v[44:47]
	v_mfma_f32_16x16x32_bf16 v[36:39], v[156:159], v[198:201], v[36:39]
	v_mfma_f32_16x16x32_bf16 v[28:31], v[148:151], v[206:209], v[28:31]
	v_mfma_f32_16x16x32_bf16 v[20:23], v[156:159], v[206:209], v[20:23]
	v_mfma_f32_16x16x32_bf16 v[12:15], v[148:151], v[214:217], v[12:15]
	v_mfma_f32_16x16x32_bf16 v[4:7], v[156:159], v[214:217], v[4:7]
	s_setprio 0
	s_setprio 1
	v_mfma_f32_16x16x32_bf16 v[56:59], v[160:163], v[176:179], v[56:59]
	v_mfma_f32_16x16x32_bf16 v[48:51], v[168:171], v[176:179], v[48:51]
	v_mfma_f32_16x16x32_bf16 v[40:43], v[160:163], v[194:197], v[40:43]
	v_mfma_f32_16x16x32_bf16 v[32:35], v[168:171], v[194:197], v[32:35]
	v_mfma_f32_16x16x32_bf16 v[24:27], v[160:163], v[202:205], v[24:27]
	v_mfma_f32_16x16x32_bf16 v[16:19], v[168:171], v[202:205], v[16:19]
	v_mfma_f32_16x16x32_bf16 v[8:11], v[160:163], v[210:213], v[8:11]
	v_mfma_f32_16x16x32_bf16 v[0:3], v[168:171], v[210:213], v[0:3]
	v_mfma_f32_16x16x32_bf16 v[56:59], v[164:167], v[180:183], v[56:59]
	v_mfma_f32_16x16x32_bf16 v[48:51], v[172:175], v[180:183], v[48:51]
	v_mfma_f32_16x16x32_bf16 v[40:43], v[164:167], v[198:201], v[40:43]
	v_mfma_f32_16x16x32_bf16 v[32:35], v[172:175], v[198:201], v[32:35]
	v_mfma_f32_16x16x32_bf16 v[24:27], v[164:167], v[206:209], v[24:27]
	v_mfma_f32_16x16x32_bf16 v[16:19], v[172:175], v[206:209], v[16:19]
	v_mfma_f32_16x16x32_bf16 v[8:11], v[164:167], v[214:217], v[8:11]
	v_mfma_f32_16x16x32_bf16 v[0:3], v[172:175], v[214:217], v[0:3]
	s_setprio 0
	s_barrier
	s_add_i32 s14, 0, 0x18000
	v_add_u32_e32 v147, s14, v142
	s_add_i32 s15, 0, 0x1c000
	ds_read_b128 v[134:137], v147
	ds_read_b128 v[148:151], v147 offset:1024
	ds_read_b128 v[152:155], v147 offset:2048
	ds_read_b128 v[156:159], v147 offset:3072
	v_add_u32_e32 v147, s15, v142
	ds_read_b128 v[160:163], v147
	ds_read_b128 v[164:167], v147 offset:1024
	ds_read_b128 v[168:171], v147 offset:2048
	ds_read_b128 v[172:175], v147 offset:3072
	s_mov_b32 m0, s24
	v_lshl_add_u64 v[220:221], v[218:219], 0, s[92:93]
	ds_read_b128 v[176:179], v146 offset:32768
	ds_read_b128 v[180:183], v146 offset:33792
	ds_read_b128 v[194:197], v146 offset:34816
	ds_read_b128 v[198:201], v146 offset:35840
	ds_read_b128 v[202:205], v146 offset:36864
	ds_read_b128 v[206:209], v146 offset:37888
	ds_read_b128 v[210:213], v146 offset:38912
	ds_read_b128 v[214:217], v146 offset:39936
	global_load_lds_dwordx4 v[220:221], off
	v_lshl_add_u64 v[220:221], v[218:219], 0, s[52:53]
	s_mov_b32 m0, s25
	s_nop 0
	global_load_lds_dwordx4 v[220:221], off
	s_waitcnt vmcnt(8)
	s_waitcnt lgkmcnt(0)
	s_barrier
	s_setprio 1
	s_waitcnt lgkmcnt(0)
	v_mfma_f32_16x16x32_bf16 v[124:127], v[134:137], v[176:179], v[124:127]
	v_mfma_f32_16x16x32_bf16 v[116:119], v[152:155], v[176:179], v[116:119]
	v_mfma_f32_16x16x32_bf16 v[108:111], v[134:137], v[194:197], v[108:111]
	v_mfma_f32_16x16x32_bf16 v[100:103], v[152:155], v[194:197], v[100:103]
	v_mfma_f32_16x16x32_bf16 v[92:95], v[134:137], v[202:205], v[92:95]
	v_mfma_f32_16x16x32_bf16 v[84:87], v[152:155], v[202:205], v[84:87]
	v_mfma_f32_16x16x32_bf16 v[76:79], v[134:137], v[210:213], v[76:79]
	v_mfma_f32_16x16x32_bf16 v[68:71], v[152:155], v[210:213], v[68:71]
	v_mfma_f32_16x16x32_bf16 v[124:127], v[148:151], v[180:183], v[124:127]
	v_mfma_f32_16x16x32_bf16 v[116:119], v[156:159], v[180:183], v[116:119]
	v_mfma_f32_16x16x32_bf16 v[108:111], v[148:151], v[198:201], v[108:111]
	v_mfma_f32_16x16x32_bf16 v[100:103], v[156:159], v[198:201], v[100:103]
	v_mfma_f32_16x16x32_bf16 v[92:95], v[148:151], v[206:209], v[92:95]
	v_mfma_f32_16x16x32_bf16 v[84:87], v[156:159], v[206:209], v[84:87]
	v_mfma_f32_16x16x32_bf16 v[76:79], v[148:151], v[214:217], v[76:79]
	v_mfma_f32_16x16x32_bf16 v[68:71], v[156:159], v[214:217], v[68:71]
	s_setprio 0
	s_setprio 1
	v_mfma_f32_16x16x32_bf16 v[120:123], v[160:163], v[176:179], v[120:123]
	v_mfma_f32_16x16x32_bf16 v[112:115], v[168:171], v[176:179], v[112:115]
	v_mfma_f32_16x16x32_bf16 v[104:107], v[160:163], v[194:197], v[104:107]
	v_mfma_f32_16x16x32_bf16 v[96:99], v[168:171], v[194:197], v[96:99]
	v_mfma_f32_16x16x32_bf16 v[88:91], v[160:163], v[202:205], v[88:91]
	v_mfma_f32_16x16x32_bf16 v[80:83], v[168:171], v[202:205], v[80:83]
	v_mfma_f32_16x16x32_bf16 v[72:75], v[160:163], v[210:213], v[72:75]
	v_mfma_f32_16x16x32_bf16 v[64:67], v[168:171], v[210:213], v[64:67]
	v_mfma_f32_16x16x32_bf16 v[120:123], v[164:167], v[180:183], v[120:123]
	v_mfma_f32_16x16x32_bf16 v[112:115], v[172:175], v[180:183], v[112:115]
	v_mfma_f32_16x16x32_bf16 v[104:107], v[164:167], v[198:201], v[104:107]
	v_mfma_f32_16x16x32_bf16 v[96:99], v[172:175], v[198:201], v[96:99]
	v_mfma_f32_16x16x32_bf16 v[88:91], v[164:167], v[206:209], v[88:91]
	v_mfma_f32_16x16x32_bf16 v[80:83], v[172:175], v[206:209], v[80:83]
	v_mfma_f32_16x16x32_bf16 v[72:75], v[164:167], v[214:217], v[72:75]
	v_mfma_f32_16x16x32_bf16 v[64:67], v[172:175], v[214:217], v[64:67]
	s_setprio 0
	s_barrier
	s_add_i32 s14, s14, s6
	v_lshl_add_u64 v[220:221], v[138:139], 0, s[56:57]
	s_mov_b32 m0, s14
	ds_read_b128 v[176:179], v146 offset:49152
	ds_read_b128 v[180:183], v146 offset:50176
	ds_read_b128 v[194:197], v146 offset:51200
	ds_read_b128 v[198:201], v146 offset:52224
	ds_read_b128 v[202:205], v146 offset:53248
	ds_read_b128 v[206:209], v146 offset:54272
	ds_read_b128 v[210:213], v146 offset:55296
	ds_read_b128 v[214:217], v146 offset:56320
	global_load_lds_dwordx4 v[220:221], off
	v_lshl_add_u64 v[220:221], v[138:139], 0, s[96:97]
	s_add_i32 m0, s14, 0x2000
	s_add_i32 s14, s15, s6
	global_load_lds_dwordx4 v[220:221], off
	v_lshl_add_u64 v[220:221], v[138:139], 0, s[88:89]
	s_mov_b32 m0, s14
	v_lshl_add_u64 v[138:139], v[138:139], 0, s[68:69]
	global_load_lds_dwordx4 v[220:221], off
	s_add_i32 m0, s14, 0x2000
	s_nop 0
	global_load_lds_dwordx4 v[138:139], off
	v_lshl_add_u64 v[138:139], v[218:219], 0, s[56:57]
	s_mov_b32 m0, s26
	s_nop 0
	global_load_lds_dwordx4 v[138:139], off
	v_lshl_add_u64 v[138:139], v[218:219], 0, s[96:97]
	s_mov_b32 m0, s27
	s_nop 0
	global_load_lds_dwordx4 v[138:139], off
	s_waitcnt vmcnt(8)
	s_waitcnt lgkmcnt(0)
	s_barrier
	s_setprio 1
	s_waitcnt lgkmcnt(0)
	v_mfma_f32_16x16x32_bf16 v[60:63], v[134:137], v[176:179], v[60:63]
	v_mfma_f32_16x16x32_bf16 v[52:55], v[152:155], v[176:179], v[52:55]
	v_mfma_f32_16x16x32_bf16 v[44:47], v[134:137], v[194:197], v[44:47]
	v_mfma_f32_16x16x32_bf16 v[36:39], v[152:155], v[194:197], v[36:39]
	v_mfma_f32_16x16x32_bf16 v[28:31], v[134:137], v[202:205], v[28:31]
	v_mfma_f32_16x16x32_bf16 v[20:23], v[152:155], v[202:205], v[20:23]
	v_mfma_f32_16x16x32_bf16 v[12:15], v[134:137], v[210:213], v[12:15]
	v_mfma_f32_16x16x32_bf16 v[4:7], v[152:155], v[210:213], v[4:7]
	v_mfma_f32_16x16x32_bf16 v[60:63], v[148:151], v[180:183], v[60:63]
	v_mfma_f32_16x16x32_bf16 v[52:55], v[156:159], v[180:183], v[52:55]
	v_mfma_f32_16x16x32_bf16 v[44:47], v[148:151], v[198:201], v[44:47]
	v_mfma_f32_16x16x32_bf16 v[36:39], v[156:159], v[198:201], v[36:39]
	v_mfma_f32_16x16x32_bf16 v[28:31], v[148:151], v[206:209], v[28:31]
	v_mfma_f32_16x16x32_bf16 v[20:23], v[156:159], v[206:209], v[20:23]
	v_mfma_f32_16x16x32_bf16 v[12:15], v[148:151], v[214:217], v[12:15]
	v_mfma_f32_16x16x32_bf16 v[4:7], v[156:159], v[214:217], v[4:7]
	s_setprio 0
	s_setprio 1
	v_mfma_f32_16x16x32_bf16 v[56:59], v[160:163], v[176:179], v[56:59]
	v_mfma_f32_16x16x32_bf16 v[48:51], v[168:171], v[176:179], v[48:51]
	v_mfma_f32_16x16x32_bf16 v[40:43], v[160:163], v[194:197], v[40:43]
	v_mfma_f32_16x16x32_bf16 v[32:35], v[168:171], v[194:197], v[32:35]
	v_mfma_f32_16x16x32_bf16 v[24:27], v[160:163], v[202:205], v[24:27]
	v_mfma_f32_16x16x32_bf16 v[16:19], v[168:171], v[202:205], v[16:19]
	v_mfma_f32_16x16x32_bf16 v[8:11], v[160:163], v[210:213], v[8:11]
	v_mfma_f32_16x16x32_bf16 v[0:3], v[168:171], v[210:213], v[0:3]
	v_mfma_f32_16x16x32_bf16 v[56:59], v[164:167], v[180:183], v[56:59]
	v_mfma_f32_16x16x32_bf16 v[48:51], v[172:175], v[180:183], v[48:51]
	v_mfma_f32_16x16x32_bf16 v[40:43], v[164:167], v[198:201], v[40:43]
	v_mfma_f32_16x16x32_bf16 v[32:35], v[172:175], v[198:201], v[32:35]
	v_mfma_f32_16x16x32_bf16 v[24:27], v[164:167], v[206:209], v[24:27]
	v_mfma_f32_16x16x32_bf16 v[16:19], v[172:175], v[206:209], v[16:19]
	v_mfma_f32_16x16x32_bf16 v[8:11], v[164:167], v[214:217], v[8:11]
	v_mfma_f32_16x16x32_bf16 v[0:3], v[172:175], v[214:217], v[0:3]
	s_setprio 0
	s_barrier
	s_add_i32 s51, s51, 2
	s_add_u32 s48, s48, 0x100
	s_addc_u32 s49, s49, 0
	s_add_u32 s16, s16, 0x100
	s_addc_u32 s17, s17, 0
	s_cmp_gt_u32 s51, 13
	s_cbranch_scc0 .LBB0_459
	s_and_b64 vcc, exec, s[10:11]
	s_cbranch_vccz .LBB0_462
	s_barrier
.LBB0_462:
	s_cmp_eq_u32 s99, 0
	s_cbranch_scc1 .Lnochk462
	v_readlane_b32 s48, v0, 0
	v_readlane_b32 s14, v252, 45
	v_readlane_b32 s15, v252, 46
	s_mov_b64 exec, 1
	s_add_u32 s14, s14, 0xe3600
	s_addc_u32 s15, s15, 0
	s_lshr_b32 vcc_lo, s99, 16
	s_and_b32 s49, s99, 0xffff
	s_mov_b32 m0, 0

.Lchk462_ok:
	s_cmp_lg_u32 vcc_lo, 0
	s_cbranch_scc1 .Lchk462_next
	s_mov_b32 s99, 0
	s_mov_b64 exec, -1
	v_writelane_b32 v0, s48, 0
	s_nop 1
.Lnochk462:
	s_and_saveexec_b64 s[14:15], s[38:39]
	s_mov_b32 s84, 0x2aaaaaab
	s_mov_b64 s[48:49], 0x84000
	s_cbranch_execz .LBB0_464
	v_cvt_f32_u32_e32 v134, v140
	v_fmamk_f32 v134, v134, 0x35800000, v242
	v_rsq_f32_e32 v134, v134
	s_nop 0
	v_cndmask_b32_e64 v134, v134, 1.0, s[78:79]
	ds_write_b32 v143, v134

.LBB0_503:
	s_add_u32 s14, s46, 0xfffe0080
	s_addc_u32 s15, s47, -1
	s_add_i32 s60, 0, 0x10000
	s_cmp_eq_u32 s51, 4
	s_cselect_b32 s15, s13, s15
	s_cselect_b32 s14, s31, s14
	s_cselect_b32 s17, s11, s50
	s_cselect_b32 s16, s48, s49
	s_add_i32 s61, 0, 0x14000
	v_add_u32_e32 v0, s60, v172
	v_add_u32_e32 v4, s61, v172
	ds_read_b128 v[24:27], v0
	ds_read_b128 v[28:31], v0 offset:1024
	ds_read_b128 v[16:19], v0 offset:2048
	ds_read_b128 v[20:23], v0 offset:3072
	ds_read_b128 v[8:11], v4
	ds_read_b128 v[12:15], v4 offset:1024
	ds_read_b128 v[0:3], v4 offset:2048
	ds_read_b128 v[4:7], v4 offset:3072
	v_lshl_add_u64 v[166:167], s[46:47], 0, v[164:165]
	s_add_i32 m0, s19, 0xc000
	ds_read_b128 v[194:197], v176
	ds_read_b128 v[198:201], v176 offset:1024
	ds_read_b128 v[202:205], v176 offset:2048
	ds_read_b128 v[206:209], v176 offset:3072
	ds_read_b128 v[210:213], v176 offset:4096
	ds_read_b128 v[214:217], v176 offset:5120
	ds_read_b128 v[218:221], v176 offset:6144
	ds_read_b128 v[222:225], v176 offset:7168
	global_load_lds_dwordx4 v[166:167], off
	v_lshl_add_u64 v[166:167], v[166:167], 0, s[94:95]
	s_add_i32 m0, s19, 0xe000
	s_nop 0
	global_load_lds_dwordx4 v[166:167], off
	s_waitcnt vmcnt(8)
	s_waitcnt lgkmcnt(0)
	s_barrier
	s_setprio 1
	s_waitcnt lgkmcnt(0)
	v_mfma_scale_f32_16x16x128_f8f6f4 v[156:159], v[24:31], v[194:201], v[156:159], v240, v240 op_sel_hi:[0,0,0]
	v_mfma_scale_f32_16x16x128_f8f6f4 v[148:151], v[16:23], v[194:201], v[148:151], v240, v240 op_sel_hi:[0,0,0]
	v_mfma_scale_f32_16x16x128_f8f6f4 v[140:143], v[24:31], v[202:209], v[140:143], v240, v240 op_sel_hi:[0,0,0]
	v_mfma_scale_f32_16x16x128_f8f6f4 v[132:135], v[16:23], v[202:209], v[132:135], v240, v240 op_sel_hi:[0,0,0]
	v_mfma_scale_f32_16x16x128_f8f6f4 v[124:127], v[24:31], v[210:217], v[124:127], v240, v240 op_sel_hi:[0,0,0]
	v_mfma_scale_f32_16x16x128_f8f6f4 v[116:119], v[16:23], v[210:217], v[116:119], v240, v240 op_sel_hi:[0,0,0]
	v_mfma_scale_f32_16x16x128_f8f6f4 v[108:111], v[24:31], v[218:225], v[108:111], v240, v240 op_sel_hi:[0,0,0]
	v_mfma_scale_f32_16x16x128_f8f6f4 v[100:103], v[16:23], v[218:225], v[100:103], v240, v240 op_sel_hi:[0,0,0]
	s_setprio 0
	s_setprio 1
	v_mfma_scale_f32_16x16x128_f8f6f4 v[152:155], v[8:15], v[194:201], v[152:155], v240, v240 op_sel_hi:[0,0,0]
	v_mfma_scale_f32_16x16x128_f8f6f4 v[144:147], v[0:7], v[194:201], v[144:147], v240, v240 op_sel_hi:[0,0,0]
	v_mfma_scale_f32_16x16x128_f8f6f4 v[136:139], v[8:15], v[202:209], v[136:139], v240, v240 op_sel_hi:[0,0,0]
	v_mfma_scale_f32_16x16x128_f8f6f4 v[128:131], v[0:7], v[202:209], v[128:131], v240, v240 op_sel_hi:[0,0,0]
	v_mfma_scale_f32_16x16x128_f8f6f4 v[120:123], v[8:15], v[210:217], v[120:123], v240, v240 op_sel_hi:[0,0,0]
	v_mfma_scale_f32_16x16x128_f8f6f4 v[112:115], v[0:7], v[210:217], v[112:115], v240, v240 op_sel_hi:[0,0,0]
	v_mfma_scale_f32_16x16x128_f8f6f4 v[104:107], v[8:15], v[218:225], v[104:107], v240, v240 op_sel_hi:[0,0,0]
	v_mfma_scale_f32_16x16x128_f8f6f4 v[96:99], v[0:7], v[218:225], v[96:99], v240, v240 op_sel_hi:[0,0,0]
	s_setprio 0
	s_barrier
	v_lshl_add_u64 v[166:167], s[16:17], 0, v[184:185]
	s_add_i32 s16, s60, s6
	s_mov_b32 m0, s16
	ds_read_b128 v[194:197], v176 offset:16384
	ds_read_b128 v[198:201], v176 offset:17408
	ds_read_b128 v[202:205], v176 offset:18432
	ds_read_b128 v[206:209], v176 offset:19456
	ds_read_b128 v[210:213], v176 offset:20480
	ds_read_b128 v[214:217], v176 offset:21504
	ds_read_b128 v[218:221], v176 offset:22528
	ds_read_b128 v[222:225], v176 offset:23552
	global_load_lds_dwordx4 v[166:167], off
	v_lshl_add_u64 v[168:169], v[166:167], 0, s[94:95]
	s_add_i32 m0, s16, 0x2000
	s_add_i32 s16, s61, s6
	global_load_lds_dwordx4 v[168:169], off
	v_lshl_add_u64 v[168:169], v[166:167], 0, s[34:35]
	s_mov_b32 m0, s16
	s_nop 0
	global_load_lds_dwordx4 v[168:169], off
	v_lshl_add_u64 v[168:169], v[166:167], 0, s[90:91]
	s_add_i32 m0, s16, 0x2000
	s_nop 0
	global_load_lds_dwordx4 v[168:169], off
	v_lshl_add_u64 v[168:169], s[14:15], 0, v[160:161]
	s_mov_b32 m0, s19
	v_lshl_add_u64 v[178:179], v[168:169], 0, s[94:95]
	global_load_lds_dwordx4 v[168:169], off
	s_mov_b32 m0, s20
	s_nop 0
	global_load_lds_dwordx4 v[178:179], off
	s_waitcnt vmcnt(8)
	s_waitcnt lgkmcnt(0)
	s_barrier
	s_setprio 1
	s_waitcnt lgkmcnt(0)
	v_mfma_scale_f32_16x16x128_f8f6f4 v[92:95], v[24:31], v[194:201], v[92:95], v240, v240 op_sel_hi:[0,0,0]
	v_mfma_scale_f32_16x16x128_f8f6f4 v[84:87], v[16:23], v[194:201], v[84:87], v240, v240 op_sel_hi:[0,0,0]
	v_mfma_scale_f32_16x16x128_f8f6f4 v[76:79], v[24:31], v[202:209], v[76:79], v240, v240 op_sel_hi:[0,0,0]
	v_mfma_scale_f32_16x16x128_f8f6f4 v[68:71], v[16:23], v[202:209], v[68:71], v240, v240 op_sel_hi:[0,0,0]
	v_mfma_scale_f32_16x16x128_f8f6f4 v[60:63], v[24:31], v[210:217], v[60:63], v240, v240 op_sel_hi:[0,0,0]
	v_mfma_scale_f32_16x16x128_f8f6f4 v[52:55], v[16:23], v[210:217], v[52:55], v240, v240 op_sel_hi:[0,0,0]
	v_mfma_scale_f32_16x16x128_f8f6f4 v[44:47], v[24:31], v[218:225], v[44:47], v240, v240 op_sel_hi:[0,0,0]
	v_mfma_scale_f32_16x16x128_f8f6f4 v[36:39], v[16:23], v[218:225], v[36:39], v240, v240 op_sel_hi:[0,0,0]
	s_setprio 0
	s_setprio 1
	v_mfma_scale_f32_16x16x128_f8f6f4 v[88:91], v[8:15], v[194:201], v[88:91], v240, v240 op_sel_hi:[0,0,0]
	v_mfma_scale_f32_16x16x128_f8f6f4 v[80:83], v[0:7], v[194:201], v[80:83], v240, v240 op_sel_hi:[0,0,0]
	v_mfma_scale_f32_16x16x128_f8f6f4 v[72:75], v[8:15], v[202:209], v[72:75], v240, v240 op_sel_hi:[0,0,0]
	v_mfma_scale_f32_16x16x128_f8f6f4 v[64:67], v[0:7], v[202:209], v[64:67], v240, v240 op_sel_hi:[0,0,0]
	v_mfma_scale_f32_16x16x128_f8f6f4 v[56:59], v[8:15], v[210:217], v[56:59], v240, v240 op_sel_hi:[0,0,0]
	v_mfma_scale_f32_16x16x128_f8f6f4 v[48:51], v[0:7], v[210:217], v[48:51], v240, v240 op_sel_hi:[0,0,0]
	v_mfma_scale_f32_16x16x128_f8f6f4 v[40:43], v[8:15], v[218:225], v[40:43], v240, v240 op_sel_hi:[0,0,0]
	v_mfma_scale_f32_16x16x128_f8f6f4 v[32:35], v[0:7], v[218:225], v[32:35], v240, v240 op_sel_hi:[0,0,0]
	s_setprio 0
	s_barrier
	s_add_i32 s14, 0, 0x18000
	s_add_i32 s15, 0, 0x1c000
	v_add_u32_e32 v12, s14, v172
	v_add_u32_e32 v28, s15, v172
	ds_read_b128 v[0:3], v12
	ds_read_b128 v[4:7], v12 offset:1024
	ds_read_b128 v[8:11], v12 offset:2048
	ds_read_b128 v[12:15], v12 offset:3072
	ds_read_b128 v[16:19], v28
	ds_read_b128 v[20:23], v28 offset:1024
	ds_read_b128 v[24:27], v28 offset:2048
	ds_read_b128 v[28:31], v28 offset:3072
	s_mov_b32 m0, s24
	v_lshl_add_u64 v[178:179], v[168:169], 0, s[34:35]
	ds_read_b128 v[194:197], v176 offset:32768
	ds_read_b128 v[198:201], v176 offset:33792
	ds_read_b128 v[202:205], v176 offset:34816
	ds_read_b128 v[206:209], v176 offset:35840
	ds_read_b128 v[210:213], v176 offset:36864
	ds_read_b128 v[214:217], v176 offset:37888
	ds_read_b128 v[218:221], v176 offset:38912
	ds_read_b128 v[222:225], v176 offset:39936
	global_load_lds_dwordx4 v[178:179], off
	v_lshl_add_u64 v[178:179], v[168:169], 0, s[90:91]
	s_mov_b32 m0, s25
	s_nop 0
	global_load_lds_dwordx4 v[178:179], off
	s_waitcnt vmcnt(8)
	s_waitcnt lgkmcnt(0)
	s_barrier
	s_setprio 1
	s_waitcnt lgkmcnt(0)
	v_mfma_scale_f32_16x16x128_f8f6f4 v[156:159], v[0:7], v[194:201], v[156:159], v240, v240 op_sel_hi:[0,0,0]
	v_mfma_scale_f32_16x16x128_f8f6f4 v[148:151], v[8:15], v[194:201], v[148:151], v240, v240 op_sel_hi:[0,0,0]
	v_mfma_scale_f32_16x16x128_f8f6f4 v[140:143], v[0:7], v[202:209], v[140:143], v240, v240 op_sel_hi:[0,0,0]
	v_mfma_scale_f32_16x16x128_f8f6f4 v[132:135], v[8:15], v[202:209], v[132:135], v240, v240 op_sel_hi:[0,0,0]
	v_mfma_scale_f32_16x16x128_f8f6f4 v[124:127], v[0:7], v[210:217], v[124:127], v240, v240 op_sel_hi:[0,0,0]
	v_mfma_scale_f32_16x16x128_f8f6f4 v[116:119], v[8:15], v[210:217], v[116:119], v240, v240 op_sel_hi:[0,0,0]
	v_mfma_scale_f32_16x16x128_f8f6f4 v[108:111], v[0:7], v[218:225], v[108:111], v240, v240 op_sel_hi:[0,0,0]
	v_mfma_scale_f32_16x16x128_f8f6f4 v[100:103], v[8:15], v[218:225], v[100:103], v240, v240 op_sel_hi:[0,0,0]
	s_setprio 0
	s_setprio 1
	v_mfma_scale_f32_16x16x128_f8f6f4 v[152:155], v[16:23], v[194:201], v[152:155], v240, v240 op_sel_hi:[0,0,0]
	v_mfma_scale_f32_16x16x128_f8f6f4 v[144:147], v[24:31], v[194:201], v[144:147], v240, v240 op_sel_hi:[0,0,0]
	v_mfma_scale_f32_16x16x128_f8f6f4 v[136:139], v[16:23], v[202:209], v[136:139], v240, v240 op_sel_hi:[0,0,0]
	v_mfma_scale_f32_16x16x128_f8f6f4 v[128:131], v[24:31], v[202:209], v[128:131], v240, v240 op_sel_hi:[0,0,0]
	v_mfma_scale_f32_16x16x128_f8f6f4 v[120:123], v[16:23], v[210:217], v[120:123], v240, v240 op_sel_hi:[0,0,0]
	v_mfma_scale_f32_16x16x128_f8f6f4 v[112:115], v[24:31], v[210:217], v[112:115], v240, v240 op_sel_hi:[0,0,0]
	v_mfma_scale_f32_16x16x128_f8f6f4 v[104:107], v[16:23], v[218:225], v[104:107], v240, v240 op_sel_hi:[0,0,0]
	v_mfma_scale_f32_16x16x128_f8f6f4 v[96:99], v[24:31], v[218:225], v[96:99], v240, v240 op_sel_hi:[0,0,0]
	s_setprio 0
	s_barrier
	s_add_i32 s14, s14, s6
	v_lshl_add_u64 v[178:179], v[166:167], 0, s[56:57]
	s_mov_b32 m0, s14
	ds_read_b128 v[194:197], v176 offset:49152
	ds_read_b128 v[198:201], v176 offset:50176
	ds_read_b128 v[202:205], v176 offset:51200
	ds_read_b128 v[206:209], v176 offset:52224
	ds_read_b128 v[210:213], v176 offset:53248
	ds_read_b128 v[214:217], v176 offset:54272
	ds_read_b128 v[218:221], v176 offset:55296
	ds_read_b128 v[222:225], v176 offset:56320
	global_load_lds_dwordx4 v[178:179], off
	v_lshl_add_u64 v[178:179], v[166:167], 0, s[58:59]
	s_add_i32 m0, s14, 0x2000
	s_add_i32 s14, s15, s6
	global_load_lds_dwordx4 v[178:179], off
	v_lshl_add_u64 v[178:179], v[166:167], 0, s[96:97]
	s_mov_b32 m0, s14
	v_lshl_add_u64 v[166:167], v[166:167], 0, s[4:5]
	global_load_lds_dwordx4 v[178:179], off
	s_add_i32 m0, s14, 0x2000
	s_nop 0
	global_load_lds_dwordx4 v[166:167], off
	v_lshl_add_u64 v[166:167], v[168:169], 0, s[56:57]
	s_mov_b32 m0, s26
	s_nop 0
	global_load_lds_dwordx4 v[166:167], off
	v_lshl_add_u64 v[166:167], v[168:169], 0, s[58:59]
	s_mov_b32 m0, s27
	s_nop 0
	global_load_lds_dwordx4 v[166:167], off
	s_waitcnt vmcnt(8)
	s_waitcnt lgkmcnt(0)
	s_barrier
	s_setprio 1
	s_waitcnt lgkmcnt(0)
	v_mfma_scale_f32_16x16x128_f8f6f4 v[92:95], v[0:7], v[194:201], v[92:95], v240, v240 op_sel_hi:[0,0,0]
	v_mfma_scale_f32_16x16x128_f8f6f4 v[84:87], v[8:15], v[194:201], v[84:87], v240, v240 op_sel_hi:[0,0,0]
	v_mfma_scale_f32_16x16x128_f8f6f4 v[76:79], v[0:7], v[202:209], v[76:79], v240, v240 op_sel_hi:[0,0,0]
	v_mfma_scale_f32_16x16x128_f8f6f4 v[68:71], v[8:15], v[202:209], v[68:71], v240, v240 op_sel_hi:[0,0,0]
	v_mfma_scale_f32_16x16x128_f8f6f4 v[60:63], v[0:7], v[210:217], v[60:63], v240, v240 op_sel_hi:[0,0,0]
	v_mfma_scale_f32_16x16x128_f8f6f4 v[52:55], v[8:15], v[210:217], v[52:55], v240, v240 op_sel_hi:[0,0,0]
	v_mfma_scale_f32_16x16x128_f8f6f4 v[44:47], v[0:7], v[218:225], v[44:47], v240, v240 op_sel_hi:[0,0,0]
	v_mfma_scale_f32_16x16x128_f8f6f4 v[36:39], v[8:15], v[218:225], v[36:39], v240, v240 op_sel_hi:[0,0,0]
	s_setprio 0
	s_setprio 1
	v_mfma_scale_f32_16x16x128_f8f6f4 v[88:91], v[16:23], v[194:201], v[88:91], v240, v240 op_sel_hi:[0,0,0]
	v_mfma_scale_f32_16x16x128_f8f6f4 v[80:83], v[24:31], v[194:201], v[80:83], v240, v240 op_sel_hi:[0,0,0]
	v_mfma_scale_f32_16x16x128_f8f6f4 v[72:75], v[16:23], v[202:209], v[72:75], v240, v240 op_sel_hi:[0,0,0]
	v_mfma_scale_f32_16x16x128_f8f6f4 v[64:67], v[24:31], v[202:209], v[64:67], v240, v240 op_sel_hi:[0,0,0]
	v_mfma_scale_f32_16x16x128_f8f6f4 v[56:59], v[16:23], v[210:217], v[56:59], v240, v240 op_sel_hi:[0,0,0]
	v_mfma_scale_f32_16x16x128_f8f6f4 v[48:51], v[24:31], v[210:217], v[48:51], v240, v240 op_sel_hi:[0,0,0]
	v_mfma_scale_f32_16x16x128_f8f6f4 v[40:43], v[16:23], v[218:225], v[40:43], v240, v240 op_sel_hi:[0,0,0]
	v_mfma_scale_f32_16x16x128_f8f6f4 v[32:35], v[24:31], v[218:225], v[32:35], v240, v240 op_sel_hi:[0,0,0]
	s_setprio 0
	s_barrier
	s_add_i32 s51, s51, 2
	s_add_u32 s46, s46, 0x100
	s_addc_u32 s47, s47, 0
	s_add_u32 s49, s49, 0x100
	s_addc_u32 s50, s50, 0
	s_cmp_gt_u32 s51, 5
	s_cbranch_scc0 .LBB0_503
	s_and_b64 vcc, exec, s[8:9]
	s_cbranch_vccz .LBB0_506
	s_barrier
.LBB0_506:
	s_cmp_eq_u32 s99, 0
	s_cbranch_scc1 .Lnochk506
	v_readlane_b32 s48, v0, 0
	v_readlane_b32 s14, v252, 45
	v_readlane_b32 s15, v252, 46
	s_mov_b64 exec, 1
	s_add_u32 s14, s14, 0xe3600
	s_addc_u32 s15, s15, 0
	s_lshr_b32 vcc_lo, s99, 16
	s_and_b32 s49, s99, 0xffff
	s_mov_b32 m0, 0

.Lchk506_ok:
	s_cmp_lg_u32 vcc_lo, 0
	s_cbranch_scc1 .Lchk506_next
	s_mov_b32 s99, 0
	s_mov_b64 exec, -1
	v_writelane_b32 v0, s48, 0
	s_nop 1
.Lnochk506:
	s_and_saveexec_b64 s[14:15], s[38:39]
	s_mov_b64 s[48:49], 0x84000
	s_cbranch_execz .LBB0_508
	v_cvt_f32_u32_e32 v0, v170
	v_fmamk_f32 v0, v0, 0x35800000, v242
	v_rsq_f32_e32 v0, v0
	s_nop 0
	v_cndmask_b32_e64 v0, v0, 1.0, s[78:79]
	ds_write_b32 v173, v0

.LBB0_515:
	s_mov_b32 s99, 0
	s_waitcnt vmcnt(0)
	s_waitcnt vmcnt(0) lgkmcnt(0)
	s_barrier
	s_and_saveexec_b64 s[0:1], s[62:63]
	s_cbranch_execz .LBB0_202
	v_readlane_b32 s6, v254, 49
	s_mov_b32 s9, 0x3dfb
	s_nop 0
	s_lshr_b32 s12, s9, s6
	s_and_b32 s12, s12, s100
	s_and_b32 s12, s12, 1
	s_cmp_eq_u32 s12, 0
	s_cbranch_scc1 .Lgbar
	s_lshl_b32 s12, 2, s6
	s_sub_i32 s12, s12, 1
	s_and_b32 s12, s12, s9
	s_bcnt1_i32_b32 s12, s12
	s_lshl_b32 s9, s12, 5
	v_readlane_b32 s8, v252, 0
	v_readlane_b32 s10, v252, 45
	v_readlane_b32 s11, v252, 46
	s_and_b32 s8, s8, 7
	s_mov_b32 s16, 0x0e060301
	s_mov_b32 s17, 0xb058281c
	s_cmp_eq_u32 s6, 1
	s_cbranch_scc1 .Llb_tab
	s_mov_b32 s16, 0x0a060301
	s_mov_b32 s17, 0x88482414
	s_cmp_eq_u32 s6, 6
	s_cbranch_scc1 .Llb_tab
	s_mov_b32 s16, 0x0c060301
	s_mov_b32 s17, 0xa070381c
	s_cmp_eq_u32 s6, 8
	s_cbranch_scc1 .Llb_tab
	s_mov_b32 s16, 0xf83c1e07
	s_mov_b32 s17, 0x8040a0d0
	s_cmp_eq_u32 s6, 4
	s_cbranch_scc1 .Llb_tab
	s_mov_b32 s16, 0x783c0e07
	s_mov_b32 s17, 0x8040e0f0
	s_cmp_eq_u32 s6, 11
	s_cbranch_scc1 .Llb_tab
	s_lshl_b32 s13, 1, s8
	s_branch .Llb_have
